# gate epilogue: non-transcendental steps as packed f32 (v_pk_fma/add/mul) on top of v114
# speedup vs baseline: 1.0006x; 1.0006x over previous
; __device__ __forceinline__ unsigned cvt_pk_bf16(float lo, float hi) { unsigned r; asm volatile("v_cvt_pk_bf16_f32 %0, %1, %2" : "=v"(r) : "v"(lo), "v"(hi)); return r; }
; __device__ __forceinline__ float fexp2(float x) { return __builtin_amdgcn_exp2f(x); }
; __device__ __forceinline__ float frcp(float x) { return __builtin_amdgcn_rcpf(x); }
;     __device__ __forceinline__ void operator()(const f32x4 (&acc)[2][2][4][2], const Unit& u, int wr, int wc, int fr, int fq) const {
;     ...
;             const f32x4 ba0 = *(const f32x4*)(b_gate + ch), ba1 = *(const f32x4*)(b_gate + ch + 4), bs0 = *(const f32x4*)(b_gate + 1024 + ch), bs1 = *(const f32x4*)(b_gate + 1024 + ch + 4);
; #pragma unroll
;             for (int ai = 0; ai < 2; ++ai)
; #pragma unroll
;                 for (int m = 0; m < 4; ++m) {
;                     const int row = row0 + ai * 128 + m * 16;
;                     f32x4 a0 = acc[ai][0][m][0] * GSC, a1 = acc[ai][0][m][1] * GSC, s0 = acc[ai][1][m][0] * GSC, s1 = acc[ai][1][m][1] * GSC;
; #pragma unroll
;                     for (int j = 0; j < 4; ++j) { const float e0 = 1.f + fexp2(-LOG2E * (a0[j] + ba0[j])), f0 = 1.f + fexp2(-LOG2E * (s0[j] + bs0[j])), e1 = 1.f + fexp2(-LOG2E * (a1[j] + ba1[j])), f1 = 1.f + fexp2(-LOG2E * (s1[j] + bs1[j]));
;                         a0[j] = f0 * frcp(e0); s0[j] = frcp(f0); a1[j] = f1 * frcp(e1); s1[j] = frcp(f1); }
;                     v4u w; w.x = pg8::cvt_pk_bf16(a0[0], a0[1]); w.y = pg8::cvt_pk_bf16(a0[2], a0[3]); w.z = pg8::cvt_pk_bf16(a1[0], a1[1]); w.w = pg8::cvt_pk_bf16(a1[2], a1[3]);
;                     __builtin_nontemporal_store(w, (v4u*)(GA + (size_t)row * 1024 + ch));
;                     w.x = pg8::cvt_pk_bf16(s0[0], s0[1]); w.y = pg8::cvt_pk_bf16(s0[2], s0[3]); w.z = pg8::cvt_pk_bf16(s1[0], s1[1]); w.w = pg8::cvt_pk_bf16(s1[2], s1[3]);
;                     __builtin_nontemporal_store(w, (v4u*)(GS + (size_t)row * 1024 + ch));
;                 }
.LBB0_342:
	v_lshl_add_u32 v18, s66, 7, v188
	v_ashrrev_i32_e32 v19, 31, v18
	v_lshlrev_b64 v[2:3], 2, v[18:19]
	v_lshl_add_u64 v[4:5], s[18:19], 0, v[2:3]
	v_lshl_add_u64 v[2:3], s[40:41], 0, v[2:3]
	global_load_dwordx4 v[14:17], v[4:5], off
	global_load_dwordx4 v[10:13], v[2:3], off
	global_load_dwordx4 v[6:9], v[4:5], off offset:16
	s_nop 0
	global_load_dwordx4 v[2:5], v[2:3], off offset:16
	v_add_u32_e32 v22, s47, v163
	v_lshlrev_b64 v[18:19], 1, v[18:19]
	v_ashrrev_i32_e32 v23, 31, v22
	v_lshlrev_b64 v[22:23], 11, v[22:23]
	v_lshl_add_u64 v[22:23], v[22:23], 0, v[18:19]
	v_mov_b32_e32 v236, 0xbd38aa3b
	v_mov_b32_e32 v240, 0x28000
	v_mov_b32_e32 v241, 0
	s_mov_b64 s[0:1], 0x8000
	s_waitcnt vmcnt(0)
	v_mul_f32_e32 v2, 0xbfb8aa3b, v2
	v_mul_f32_e32 v3, 0xbfb8aa3b, v3
	v_mul_f32_e32 v4, 0xbfb8aa3b, v4
	v_mul_f32_e32 v5, 0xbfb8aa3b, v5
	v_mul_f32_e32 v6, 0xbfb8aa3b, v6
	v_mul_f32_e32 v7, 0xbfb8aa3b, v7
	v_mul_f32_e32 v8, 0xbfb8aa3b, v8
	v_mul_f32_e32 v9, 0xbfb8aa3b, v9
	v_mul_f32_e32 v10, 0xbfb8aa3b, v10
	v_mul_f32_e32 v11, 0xbfb8aa3b, v11
	v_mul_f32_e32 v12, 0xbfb8aa3b, v12
	v_mul_f32_e32 v13, 0xbfb8aa3b, v13
	v_mul_f32_e32 v14, 0xbfb8aa3b, v14
	v_mul_f32_e32 v15, 0xbfb8aa3b, v15
	v_mul_f32_e32 v16, 0xbfb8aa3b, v16
	v_mul_f32_e32 v17, 0xbfb8aa3b, v17
	v_lshl_add_u64 v[24:25], s[24:25], 0, v[22:23]
	v_lshl_add_u64 v[238:239], s[26:27], 0, v[22:23]
	v_pk_fma_f32 v[150:151], v[150:151], v[236:237], v[14:15] op_sel_hi:[1,0,1]
	v_pk_fma_f32 v[152:153], v[152:153], v[236:237], v[16:17] op_sel_hi:[1,0,1]
	v_pk_fma_f32 v[146:147], v[146:147], v[236:237], v[6:7] op_sel_hi:[1,0,1]
	v_pk_fma_f32 v[148:149], v[148:149], v[236:237], v[8:9] op_sel_hi:[1,0,1]
	v_pk_fma_f32 v[142:143], v[142:143], v[236:237], v[10:11] op_sel_hi:[1,0,1]
	v_pk_fma_f32 v[144:145], v[144:145], v[236:237], v[12:13] op_sel_hi:[1,0,1]
	v_pk_fma_f32 v[138:139], v[138:139], v[236:237], v[2:3] op_sel_hi:[1,0,1]
	v_pk_fma_f32 v[140:141], v[140:141], v[236:237], v[4:5] op_sel_hi:[1,0,1]
	v_exp_f32_e32 v150, v150
	v_exp_f32_e32 v151, v151
	v_exp_f32_e32 v152, v152
	v_exp_f32_e32 v153, v153
	v_exp_f32_e32 v146, v146
	v_exp_f32_e32 v147, v147
	v_exp_f32_e32 v148, v148
	v_exp_f32_e32 v149, v149
	v_exp_f32_e32 v142, v142
	v_exp_f32_e32 v143, v143
	v_exp_f32_e32 v144, v144
	v_exp_f32_e32 v145, v145
	v_exp_f32_e32 v138, v138
	v_exp_f32_e32 v139, v139
	v_exp_f32_e32 v140, v140
	v_exp_f32_e32 v141, v141
	v_pk_add_f32 v[150:151], v[150:151], 1.0 op_sel_hi:[1,0]
	v_pk_add_f32 v[152:153], v[152:153], 1.0 op_sel_hi:[1,0]
	v_pk_add_f32 v[146:147], v[146:147], 1.0 op_sel_hi:[1,0]
	v_pk_add_f32 v[148:149], v[148:149], 1.0 op_sel_hi:[1,0]
	v_pk_add_f32 v[142:143], v[142:143], 1.0 op_sel_hi:[1,0]
	v_pk_add_f32 v[144:145], v[144:145], 1.0 op_sel_hi:[1,0]
	v_pk_add_f32 v[138:139], v[138:139], 1.0 op_sel_hi:[1,0]
	v_pk_add_f32 v[140:141], v[140:141], 1.0 op_sel_hi:[1,0]
	v_rcp_f32_e32 v150, v150
	v_rcp_f32_e32 v151, v151
	v_rcp_f32_e32 v152, v152
	v_rcp_f32_e32 v153, v153
	v_rcp_f32_e32 v146, v146
	v_rcp_f32_e32 v147, v147
	v_rcp_f32_e32 v148, v148
	v_rcp_f32_e32 v149, v149
	v_pk_mul_f32 v[150:151], v[142:143], v[150:151]
	v_pk_mul_f32 v[152:153], v[144:145], v[152:153]
	v_pk_mul_f32 v[146:147], v[138:139], v[146:147]
	v_pk_mul_f32 v[148:149], v[140:141], v[148:149]
	v_rcp_f32_e32 v142, v142
	v_rcp_f32_e32 v143, v143
	v_rcp_f32_e32 v144, v144
	v_rcp_f32_e32 v145, v145
	v_rcp_f32_e32 v138, v138
	v_rcp_f32_e32 v139, v139
	v_rcp_f32_e32 v140, v140
	v_rcp_f32_e32 v141, v141
	v_cvt_pk_bf16_f32 v150, v150, v151
	v_cvt_pk_bf16_f32 v151, v152, v153
	v_cvt_pk_bf16_f32 v152, v146, v147
	v_cvt_pk_bf16_f32 v153, v148, v149
	global_store_dwordx4 v[24:25], v[150:153], off nt
	v_cvt_pk_bf16_f32 v142, v142, v143
	v_cvt_pk_bf16_f32 v143, v144, v145
	v_cvt_pk_bf16_f32 v144, v138, v139
	v_cvt_pk_bf16_f32 v145, v140, v141
	global_store_dwordx4 v[238:239], v[142:145], off nt
	v_lshl_add_u64 v[22:23], v[22:23], 0, s[0:1]
	v_lshl_add_u64 v[24:25], s[24:25], 0, v[22:23]
	v_lshl_add_u64 v[238:239], s[26:27], 0, v[22:23]
	v_pk_fma_f32 v[134:135], v[134:135], v[236:237], v[14:15] op_sel_hi:[1,0,1]
	v_pk_fma_f32 v[136:137], v[136:137], v[236:237], v[16:17] op_sel_hi:[1,0,1]
	v_pk_fma_f32 v[130:131], v[130:131], v[236:237], v[6:7] op_sel_hi:[1,0,1]
	v_pk_fma_f32 v[132:133], v[132:133], v[236:237], v[8:9] op_sel_hi:[1,0,1]
	v_pk_fma_f32 v[126:127], v[126:127], v[236:237], v[10:11] op_sel_hi:[1,0,1]
	v_pk_fma_f32 v[128:129], v[128:129], v[236:237], v[12:13] op_sel_hi:[1,0,1]
	v_pk_fma_f32 v[122:123], v[122:123], v[236:237], v[2:3] op_sel_hi:[1,0,1]
	v_pk_fma_f32 v[124:125], v[124:125], v[236:237], v[4:5] op_sel_hi:[1,0,1]
	v_exp_f32_e32 v134, v134
	v_exp_f32_e32 v135, v135
	v_exp_f32_e32 v136, v136
	v_exp_f32_e32 v137, v137
	v_exp_f32_e32 v130, v130
	v_exp_f32_e32 v131, v131
	v_exp_f32_e32 v132, v132
	v_exp_f32_e32 v133, v133
	v_exp_f32_e32 v126, v126
	v_exp_f32_e32 v127, v127
	v_exp_f32_e32 v128, v128
	v_exp_f32_e32 v129, v129
	v_exp_f32_e32 v122, v122
	v_exp_f32_e32 v123, v123
	v_exp_f32_e32 v124, v124
	v_exp_f32_e32 v125, v125
	v_pk_add_f32 v[134:135], v[134:135], 1.0 op_sel_hi:[1,0]
	v_pk_add_f32 v[136:137], v[136:137], 1.0 op_sel_hi:[1,0]
	v_pk_add_f32 v[130:131], v[130:131], 1.0 op_sel_hi:[1,0]
	v_pk_add_f32 v[132:133], v[132:133], 1.0 op_sel_hi:[1,0]
	v_pk_add_f32 v[126:127], v[126:127], 1.0 op_sel_hi:[1,0]
	v_pk_add_f32 v[128:129], v[128:129], 1.0 op_sel_hi:[1,0]
	v_pk_add_f32 v[122:123], v[122:123], 1.0 op_sel_hi:[1,0]
	v_pk_add_f32 v[124:125], v[124:125], 1.0 op_sel_hi:[1,0]
	v_rcp_f32_e32 v134, v134
	v_rcp_f32_e32 v135, v135
	v_rcp_f32_e32 v136, v136
	v_rcp_f32_e32 v137, v137
	v_rcp_f32_e32 v130, v130
	v_rcp_f32_e32 v131, v131
; __device__ __forceinline__ unsigned cvt_pk_bf16(float lo, float hi) { unsigned r; asm volatile("v_cvt_pk_bf16_f32 %0, %1, %2" : "=v"(r) : "v"(lo), "v"(hi)); return r; }
; __device__ __forceinline__ float fexp2(float x) { return __builtin_amdgcn_exp2f(x); }
; __device__ __forceinline__ float frcp(float x) { return __builtin_amdgcn_rcpf(x); }
;     __device__ __forceinline__ void operator()(const f32x4 (&acc)[2][2][4][2], const Unit& u, int wr, int wc, int fr, int fq) const {
;     ...
;             const f32x4 ba0 = *(const f32x4*)(b_gate + ch), ba1 = *(const f32x4*)(b_gate + ch + 4), bs0 = *(const f32x4*)(b_gate + 1024 + ch), bs1 = *(const f32x4*)(b_gate + 1024 + ch + 4);
; #pragma unroll
;             for (int ai = 0; ai < 2; ++ai)
; #pragma unroll
;                 for (int m = 0; m < 4; ++m) {
;                     const int row = row0 + ai * 128 + m * 16;
;                     f32x4 a0 = acc[ai][0][m][0] * GSC, a1 = acc[ai][0][m][1] * GSC, s0 = acc[ai][1][m][0] * GSC, s1 = acc[ai][1][m][1] * GSC;
; #pragma unroll
;                     for (int j = 0; j < 4; ++j) { const float e0 = 1.f + fexp2(-LOG2E * (a0[j] + ba0[j])), f0 = 1.f + fexp2(-LOG2E * (s0[j] + bs0[j])), e1 = 1.f + fexp2(-LOG2E * (a1[j] + ba1[j])), f1 = 1.f + fexp2(-LOG2E * (s1[j] + bs1[j]));
;                         a0[j] = f0 * frcp(e0); s0[j] = frcp(f0); a1[j] = f1 * frcp(e1); s1[j] = frcp(f1); }
;                     v4u w; w.x = pg8::cvt_pk_bf16(a0[0], a0[1]); w.y = pg8::cvt_pk_bf16(a0[2], a0[3]); w.z = pg8::cvt_pk_bf16(a1[0], a1[1]); w.w = pg8::cvt_pk_bf16(a1[2], a1[3]);
;                     __builtin_nontemporal_store(w, (v4u*)(GA + (size_t)row * 1024 + ch));
;                     w.x = pg8::cvt_pk_bf16(s0[0], s0[1]); w.y = pg8::cvt_pk_bf16(s0[2], s0[3]); w.z = pg8::cvt_pk_bf16(s1[0], s1[1]); w.w = pg8::cvt_pk_bf16(s1[2], s1[3]);
;                     __builtin_nontemporal_store(w, (v4u*)(GS + (size_t)row * 1024 + ch));
;                 }
	v_rcp_f32_e32 v132, v132
	v_rcp_f32_e32 v133, v133
	v_pk_mul_f32 v[134:135], v[126:127], v[134:135]
	v_pk_mul_f32 v[136:137], v[128:129], v[136:137]
	v_pk_mul_f32 v[130:131], v[122:123], v[130:131]
	v_pk_mul_f32 v[132:133], v[124:125], v[132:133]
	v_rcp_f32_e32 v126, v126
	v_rcp_f32_e32 v127, v127
	v_rcp_f32_e32 v128, v128
	v_rcp_f32_e32 v129, v129
	v_rcp_f32_e32 v122, v122
	v_rcp_f32_e32 v123, v123
	v_rcp_f32_e32 v124, v124
	v_rcp_f32_e32 v125, v125
	v_cvt_pk_bf16_f32 v134, v134, v135
	v_cvt_pk_bf16_f32 v135, v136, v137
	v_cvt_pk_bf16_f32 v136, v130, v131
	v_cvt_pk_bf16_f32 v137, v132, v133
	global_store_dwordx4 v[24:25], v[134:137], off nt
	v_cvt_pk_bf16_f32 v126, v126, v127
	v_cvt_pk_bf16_f32 v127, v128, v129
	v_cvt_pk_bf16_f32 v128, v122, v123
	v_cvt_pk_bf16_f32 v129, v124, v125
	global_store_dwordx4 v[238:239], v[126:129], off nt
	v_lshl_add_u64 v[22:23], v[22:23], 0, s[0:1]
	v_lshl_add_u64 v[24:25], s[24:25], 0, v[22:23]
	v_lshl_add_u64 v[238:239], s[26:27], 0, v[22:23]
	v_pk_fma_f32 v[118:119], v[118:119], v[236:237], v[14:15] op_sel_hi:[1,0,1]
	v_pk_fma_f32 v[120:121], v[120:121], v[236:237], v[16:17] op_sel_hi:[1,0,1]
	v_pk_fma_f32 v[114:115], v[114:115], v[236:237], v[6:7] op_sel_hi:[1,0,1]
	v_pk_fma_f32 v[116:117], v[116:117], v[236:237], v[8:9] op_sel_hi:[1,0,1]
	v_pk_fma_f32 v[110:111], v[110:111], v[236:237], v[10:11] op_sel_hi:[1,0,1]
	v_pk_fma_f32 v[112:113], v[112:113], v[236:237], v[12:13] op_sel_hi:[1,0,1]
	v_pk_fma_f32 v[106:107], v[106:107], v[236:237], v[2:3] op_sel_hi:[1,0,1]
	v_pk_fma_f32 v[108:109], v[108:109], v[236:237], v[4:5] op_sel_hi:[1,0,1]
	v_exp_f32_e32 v118, v118
	v_exp_f32_e32 v119, v119
	v_exp_f32_e32 v120, v120
	v_exp_f32_e32 v121, v121
	v_exp_f32_e32 v114, v114
	v_exp_f32_e32 v115, v115
	v_exp_f32_e32 v116, v116
	v_exp_f32_e32 v117, v117
	v_exp_f32_e32 v110, v110
	v_exp_f32_e32 v111, v111
	v_exp_f32_e32 v112, v112
	v_exp_f32_e32 v113, v113
	v_exp_f32_e32 v106, v106
	v_exp_f32_e32 v107, v107
	v_exp_f32_e32 v108, v108
	v_exp_f32_e32 v109, v109
	v_pk_add_f32 v[118:119], v[118:119], 1.0 op_sel_hi:[1,0]
	v_pk_add_f32 v[120:121], v[120:121], 1.0 op_sel_hi:[1,0]
	v_pk_add_f32 v[114:115], v[114:115], 1.0 op_sel_hi:[1,0]
	v_pk_add_f32 v[116:117], v[116:117], 1.0 op_sel_hi:[1,0]
	v_pk_add_f32 v[110:111], v[110:111], 1.0 op_sel_hi:[1,0]
	v_pk_add_f32 v[112:113], v[112:113], 1.0 op_sel_hi:[1,0]
	v_pk_add_f32 v[106:107], v[106:107], 1.0 op_sel_hi:[1,0]
	v_pk_add_f32 v[108:109], v[108:109], 1.0 op_sel_hi:[1,0]
	v_rcp_f32_e32 v118, v118
	v_rcp_f32_e32 v119, v119
	v_rcp_f32_e32 v120, v120
	v_rcp_f32_e32 v121, v121
	v_rcp_f32_e32 v114, v114
	v_rcp_f32_e32 v115, v115
	v_rcp_f32_e32 v116, v116
	v_rcp_f32_e32 v117, v117
	v_pk_mul_f32 v[118:119], v[110:111], v[118:119]
	v_pk_mul_f32 v[120:121], v[112:113], v[120:121]
	v_pk_mul_f32 v[114:115], v[106:107], v[114:115]
	v_pk_mul_f32 v[116:117], v[108:109], v[116:117]
	v_rcp_f32_e32 v110, v110
	v_rcp_f32_e32 v111, v111
	v_rcp_f32_e32 v112, v112
	v_rcp_f32_e32 v113, v113
	v_rcp_f32_e32 v106, v106
	v_rcp_f32_e32 v107, v107
	v_rcp_f32_e32 v108, v108
	v_rcp_f32_e32 v109, v109
	v_cvt_pk_bf16_f32 v118, v118, v119
	v_cvt_pk_bf16_f32 v119, v120, v121
	v_cvt_pk_bf16_f32 v120, v114, v115
	v_cvt_pk_bf16_f32 v121, v116, v117
	global_store_dwordx4 v[24:25], v[118:121], off nt
	v_cvt_pk_bf16_f32 v110, v110, v111
	v_cvt_pk_bf16_f32 v111, v112, v113
	v_cvt_pk_bf16_f32 v112, v106, v107
	v_cvt_pk_bf16_f32 v113, v108, v109
	global_store_dwordx4 v[238:239], v[110:113], off nt
	v_lshl_add_u64 v[22:23], v[22:23], 0, s[0:1]
	v_lshl_add_u64 v[24:25], s[24:25], 0, v[22:23]
	v_lshl_add_u64 v[238:239], s[26:27], 0, v[22:23]
	v_pk_fma_f32 v[102:103], v[102:103], v[236:237], v[14:15] op_sel_hi:[1,0,1]
	v_pk_fma_f32 v[104:105], v[104:105], v[236:237], v[16:17] op_sel_hi:[1,0,1]
	v_pk_fma_f32 v[98:99], v[98:99], v[236:237], v[6:7] op_sel_hi:[1,0,1]
	v_pk_fma_f32 v[100:101], v[100:101], v[236:237], v[8:9] op_sel_hi:[1,0,1]
	v_pk_fma_f32 v[94:95], v[94:95], v[236:237], v[10:11] op_sel_hi:[1,0,1]
	v_pk_fma_f32 v[96:97], v[96:97], v[236:237], v[12:13] op_sel_hi:[1,0,1]
	v_pk_fma_f32 v[90:91], v[90:91], v[236:237], v[2:3] op_sel_hi:[1,0,1]
	v_pk_fma_f32 v[92:93], v[92:93], v[236:237], v[4:5] op_sel_hi:[1,0,1]
	v_exp_f32_e32 v102, v102
	v_exp_f32_e32 v103, v103
	v_exp_f32_e32 v104, v104
	v_exp_f32_e32 v105, v105
	v_exp_f32_e32 v98, v98
	v_exp_f32_e32 v99, v99
	v_exp_f32_e32 v100, v100
	v_exp_f32_e32 v101, v101
	v_exp_f32_e32 v94, v94
	v_exp_f32_e32 v95, v95
	v_exp_f32_e32 v96, v96
	v_exp_f32_e32 v97, v97
	v_exp_f32_e32 v90, v90
	v_exp_f32_e32 v91, v91
	v_exp_f32_e32 v92, v92
	v_exp_f32_e32 v93, v93
	v_pk_add_f32 v[102:103], v[102:103], 1.0 op_sel_hi:[1,0]
	v_pk_add_f32 v[104:105], v[104:105], 1.0 op_sel_hi:[1,0]
	v_pk_add_f32 v[98:99], v[98:99], 1.0 op_sel_hi:[1,0]
	v_pk_add_f32 v[100:101], v[100:101], 1.0 op_sel_hi:[1,0]
	v_pk_add_f32 v[94:95], v[94:95], 1.0 op_sel_hi:[1,0]
	v_pk_add_f32 v[96:97], v[96:97], 1.0 op_sel_hi:[1,0]
	v_pk_add_f32 v[90:91], v[90:91], 1.0 op_sel_hi:[1,0]
	v_pk_add_f32 v[92:93], v[92:93], 1.0 op_sel_hi:[1,0]
	v_rcp_f32_e32 v102, v102
	v_rcp_f32_e32 v103, v103
	v_rcp_f32_e32 v104, v104
	v_rcp_f32_e32 v105, v105
	v_rcp_f32_e32 v98, v98
	v_rcp_f32_e32 v99, v99
	v_rcp_f32_e32 v100, v100
	v_rcp_f32_e32 v101, v101
	v_pk_mul_f32 v[102:103], v[94:95], v[102:103]
	v_pk_mul_f32 v[104:105], v[96:97], v[104:105]
	v_pk_mul_f32 v[98:99], v[90:91], v[98:99]
	v_pk_mul_f32 v[100:101], v[92:93], v[100:101]
	v_rcp_f32_e32 v94, v94
	v_rcp_f32_e32 v95, v95
	v_rcp_f32_e32 v96, v96
	v_rcp_f32_e32 v97, v97
	v_rcp_f32_e32 v90, v90
	v_rcp_f32_e32 v91, v91
	v_rcp_f32_e32 v92, v92
	v_rcp_f32_e32 v93, v93
; __device__ __forceinline__ unsigned cvt_pk_bf16(float lo, float hi) { unsigned r; asm volatile("v_cvt_pk_bf16_f32 %0, %1, %2" : "=v"(r) : "v"(lo), "v"(hi)); return r; }
; __device__ __forceinline__ float fexp2(float x) { return __builtin_amdgcn_exp2f(x); }
; __device__ __forceinline__ float frcp(float x) { return __builtin_amdgcn_rcpf(x); }
;     __device__ __forceinline__ void operator()(const f32x4 (&acc)[2][2][4][2], const Unit& u, int wr, int wc, int fr, int fq) const {
;     ...
;             const f32x4 ba0 = *(const f32x4*)(b_gate + ch), ba1 = *(const f32x4*)(b_gate + ch + 4), bs0 = *(const f32x4*)(b_gate + 1024 + ch), bs1 = *(const f32x4*)(b_gate + 1024 + ch + 4);
; #pragma unroll
;             for (int ai = 0; ai < 2; ++ai)
; #pragma unroll
;                 for (int m = 0; m < 4; ++m) {
;                     const int row = row0 + ai * 128 + m * 16;
;                     f32x4 a0 = acc[ai][0][m][0] * GSC, a1 = acc[ai][0][m][1] * GSC, s0 = acc[ai][1][m][0] * GSC, s1 = acc[ai][1][m][1] * GSC;
; #pragma unroll
;                     for (int j = 0; j < 4; ++j) { const float e0 = 1.f + fexp2(-LOG2E * (a0[j] + ba0[j])), f0 = 1.f + fexp2(-LOG2E * (s0[j] + bs0[j])), e1 = 1.f + fexp2(-LOG2E * (a1[j] + ba1[j])), f1 = 1.f + fexp2(-LOG2E * (s1[j] + bs1[j]));
;                         a0[j] = f0 * frcp(e0); s0[j] = frcp(f0); a1[j] = f1 * frcp(e1); s1[j] = frcp(f1); }
;                     v4u w; w.x = pg8::cvt_pk_bf16(a0[0], a0[1]); w.y = pg8::cvt_pk_bf16(a0[2], a0[3]); w.z = pg8::cvt_pk_bf16(a1[0], a1[1]); w.w = pg8::cvt_pk_bf16(a1[2], a1[3]);
;                     __builtin_nontemporal_store(w, (v4u*)(GA + (size_t)row * 1024 + ch));
;                     w.x = pg8::cvt_pk_bf16(s0[0], s0[1]); w.y = pg8::cvt_pk_bf16(s0[2], s0[3]); w.z = pg8::cvt_pk_bf16(s1[0], s1[1]); w.w = pg8::cvt_pk_bf16(s1[2], s1[3]);
;                     __builtin_nontemporal_store(w, (v4u*)(GS + (size_t)row * 1024 + ch));
;                 }
	v_cvt_pk_bf16_f32 v102, v102, v103
	v_cvt_pk_bf16_f32 v103, v104, v105
	v_cvt_pk_bf16_f32 v104, v98, v99
	v_cvt_pk_bf16_f32 v105, v100, v101
	global_store_dwordx4 v[24:25], v[102:105], off nt
	v_cvt_pk_bf16_f32 v94, v94, v95
	v_cvt_pk_bf16_f32 v95, v96, v97
	v_cvt_pk_bf16_f32 v96, v90, v91
	v_cvt_pk_bf16_f32 v97, v92, v93
	global_store_dwordx4 v[238:239], v[94:97], off nt
	v_lshl_add_u64 v[22:23], v[22:23], 0, v[240:241]
	v_lshl_add_u64 v[24:25], s[24:25], 0, v[22:23]
	v_lshl_add_u64 v[238:239], s[26:27], 0, v[22:23]
	v_pk_fma_f32 v[86:87], v[86:87], v[236:237], v[14:15] op_sel_hi:[1,0,1]
	v_pk_fma_f32 v[88:89], v[88:89], v[236:237], v[16:17] op_sel_hi:[1,0,1]
	v_pk_fma_f32 v[82:83], v[82:83], v[236:237], v[6:7] op_sel_hi:[1,0,1]
	v_pk_fma_f32 v[84:85], v[84:85], v[236:237], v[8:9] op_sel_hi:[1,0,1]
	v_pk_fma_f32 v[78:79], v[78:79], v[236:237], v[10:11] op_sel_hi:[1,0,1]
	v_pk_fma_f32 v[80:81], v[80:81], v[236:237], v[12:13] op_sel_hi:[1,0,1]
	v_pk_fma_f32 v[74:75], v[74:75], v[236:237], v[2:3] op_sel_hi:[1,0,1]
	v_pk_fma_f32 v[76:77], v[76:77], v[236:237], v[4:5] op_sel_hi:[1,0,1]
	v_exp_f32_e32 v86, v86
	v_exp_f32_e32 v87, v87
	v_exp_f32_e32 v88, v88
	v_exp_f32_e32 v89, v89
	v_exp_f32_e32 v82, v82
	v_exp_f32_e32 v83, v83
	v_exp_f32_e32 v84, v84
	v_exp_f32_e32 v85, v85
	v_exp_f32_e32 v78, v78
	v_exp_f32_e32 v79, v79
	v_exp_f32_e32 v80, v80
	v_exp_f32_e32 v81, v81
	v_exp_f32_e32 v74, v74
	v_exp_f32_e32 v75, v75
	v_exp_f32_e32 v76, v76
	v_exp_f32_e32 v77, v77
	v_pk_add_f32 v[86:87], v[86:87], 1.0 op_sel_hi:[1,0]
	v_pk_add_f32 v[88:89], v[88:89], 1.0 op_sel_hi:[1,0]
	v_pk_add_f32 v[82:83], v[82:83], 1.0 op_sel_hi:[1,0]
	v_pk_add_f32 v[84:85], v[84:85], 1.0 op_sel_hi:[1,0]
	v_pk_add_f32 v[78:79], v[78:79], 1.0 op_sel_hi:[1,0]
	v_pk_add_f32 v[80:81], v[80:81], 1.0 op_sel_hi:[1,0]
	v_pk_add_f32 v[74:75], v[74:75], 1.0 op_sel_hi:[1,0]
	v_pk_add_f32 v[76:77], v[76:77], 1.0 op_sel_hi:[1,0]
	v_rcp_f32_e32 v86, v86
	v_rcp_f32_e32 v87, v87
	v_rcp_f32_e32 v88, v88
	v_rcp_f32_e32 v89, v89
	v_rcp_f32_e32 v82, v82
	v_rcp_f32_e32 v83, v83
	v_rcp_f32_e32 v84, v84
	v_rcp_f32_e32 v85, v85
	v_pk_mul_f32 v[86:87], v[78:79], v[86:87]
	v_pk_mul_f32 v[88:89], v[80:81], v[88:89]
	v_pk_mul_f32 v[82:83], v[74:75], v[82:83]
	v_pk_mul_f32 v[84:85], v[76:77], v[84:85]
	v_rcp_f32_e32 v78, v78
	v_rcp_f32_e32 v79, v79
	v_rcp_f32_e32 v80, v80
	v_rcp_f32_e32 v81, v81
	v_rcp_f32_e32 v74, v74
	v_rcp_f32_e32 v75, v75
	v_rcp_f32_e32 v76, v76
	v_rcp_f32_e32 v77, v77
	v_cvt_pk_bf16_f32 v86, v86, v87
	v_cvt_pk_bf16_f32 v87, v88, v89
	v_cvt_pk_bf16_f32 v88, v82, v83
	v_cvt_pk_bf16_f32 v89, v84, v85
	global_store_dwordx4 v[24:25], v[86:89], off nt
	v_cvt_pk_bf16_f32 v78, v78, v79
	v_cvt_pk_bf16_f32 v79, v80, v81
	v_cvt_pk_bf16_f32 v80, v74, v75
	v_cvt_pk_bf16_f32 v81, v76, v77
	global_store_dwordx4 v[238:239], v[78:81], off nt
	v_lshl_add_u64 v[22:23], v[22:23], 0, s[0:1]
	v_lshl_add_u64 v[24:25], s[24:25], 0, v[22:23]
	v_lshl_add_u64 v[238:239], s[26:27], 0, v[22:23]
	v_pk_fma_f32 v[70:71], v[70:71], v[236:237], v[14:15] op_sel_hi:[1,0,1]
	v_pk_fma_f32 v[72:73], v[72:73], v[236:237], v[16:17] op_sel_hi:[1,0,1]
	v_pk_fma_f32 v[66:67], v[66:67], v[236:237], v[6:7] op_sel_hi:[1,0,1]
	v_pk_fma_f32 v[68:69], v[68:69], v[236:237], v[8:9] op_sel_hi:[1,0,1]
	v_pk_fma_f32 v[62:63], v[62:63], v[236:237], v[10:11] op_sel_hi:[1,0,1]
	v_pk_fma_f32 v[64:65], v[64:65], v[236:237], v[12:13] op_sel_hi:[1,0,1]
	v_pk_fma_f32 v[58:59], v[58:59], v[236:237], v[2:3] op_sel_hi:[1,0,1]
	v_pk_fma_f32 v[60:61], v[60:61], v[236:237], v[4:5] op_sel_hi:[1,0,1]
	v_exp_f32_e32 v70, v70
	v_exp_f32_e32 v71, v71
	v_exp_f32_e32 v72, v72
	v_exp_f32_e32 v73, v73
	v_exp_f32_e32 v66, v66
	v_exp_f32_e32 v67, v67
	v_exp_f32_e32 v68, v68
	v_exp_f32_e32 v69, v69
	v_exp_f32_e32 v62, v62
	v_exp_f32_e32 v63, v63
	v_exp_f32_e32 v64, v64
	v_exp_f32_e32 v65, v65
	v_exp_f32_e32 v58, v58
	v_exp_f32_e32 v59, v59
	v_exp_f32_e32 v60, v60
	v_exp_f32_e32 v61, v61
	v_pk_add_f32 v[70:71], v[70:71], 1.0 op_sel_hi:[1,0]
	v_pk_add_f32 v[72:73], v[72:73], 1.0 op_sel_hi:[1,0]
	v_pk_add_f32 v[66:67], v[66:67], 1.0 op_sel_hi:[1,0]
	v_pk_add_f32 v[68:69], v[68:69], 1.0 op_sel_hi:[1,0]
	v_pk_add_f32 v[62:63], v[62:63], 1.0 op_sel_hi:[1,0]
	v_pk_add_f32 v[64:65], v[64:65], 1.0 op_sel_hi:[1,0]
	v_pk_add_f32 v[58:59], v[58:59], 1.0 op_sel_hi:[1,0]
	v_pk_add_f32 v[60:61], v[60:61], 1.0 op_sel_hi:[1,0]
	v_rcp_f32_e32 v70, v70
	v_rcp_f32_e32 v71, v71
	v_rcp_f32_e32 v72, v72
	v_rcp_f32_e32 v73, v73
	v_rcp_f32_e32 v66, v66
	v_rcp_f32_e32 v67, v67
	v_rcp_f32_e32 v68, v68
	v_rcp_f32_e32 v69, v69
	v_pk_mul_f32 v[70:71], v[62:63], v[70:71]
	v_pk_mul_f32 v[72:73], v[64:65], v[72:73]
	v_pk_mul_f32 v[66:67], v[58:59], v[66:67]
	v_pk_mul_f32 v[68:69], v[60:61], v[68:69]
	v_rcp_f32_e32 v62, v62
	v_rcp_f32_e32 v63, v63
	v_rcp_f32_e32 v64, v64
	v_rcp_f32_e32 v65, v65
	v_rcp_f32_e32 v58, v58
	v_rcp_f32_e32 v59, v59
	v_rcp_f32_e32 v60, v60
	v_rcp_f32_e32 v61, v61
	v_cvt_pk_bf16_f32 v70, v70, v71
	v_cvt_pk_bf16_f32 v71, v72, v73
	v_cvt_pk_bf16_f32 v72, v66, v67
	v_cvt_pk_bf16_f32 v73, v68, v69
	global_store_dwordx4 v[24:25], v[70:73], off nt
	v_cvt_pk_bf16_f32 v62, v62, v63
; __device__ __forceinline__ unsigned cvt_pk_bf16(float lo, float hi) { unsigned r; asm volatile("v_cvt_pk_bf16_f32 %0, %1, %2" : "=v"(r) : "v"(lo), "v"(hi)); return r; }
; __device__ __forceinline__ float fexp2(float x) { return __builtin_amdgcn_exp2f(x); }
; __device__ __forceinline__ float frcp(float x) { return __builtin_amdgcn_rcpf(x); }
;     __device__ __forceinline__ void operator()(const f32x4 (&acc)[2][2][4][2], const Unit& u, int wr, int wc, int fr, int fq) const {
;     ...
;             const f32x4 ba0 = *(const f32x4*)(b_gate + ch), ba1 = *(const f32x4*)(b_gate + ch + 4), bs0 = *(const f32x4*)(b_gate + 1024 + ch), bs1 = *(const f32x4*)(b_gate + 1024 + ch + 4);
; #pragma unroll
;             for (int ai = 0; ai < 2; ++ai)
; #pragma unroll
;                 for (int m = 0; m < 4; ++m) {
;                     const int row = row0 + ai * 128 + m * 16;
;                     f32x4 a0 = acc[ai][0][m][0] * GSC, a1 = acc[ai][0][m][1] * GSC, s0 = acc[ai][1][m][0] * GSC, s1 = acc[ai][1][m][1] * GSC;
; #pragma unroll
;                     for (int j = 0; j < 4; ++j) { const float e0 = 1.f + fexp2(-LOG2E * (a0[j] + ba0[j])), f0 = 1.f + fexp2(-LOG2E * (s0[j] + bs0[j])), e1 = 1.f + fexp2(-LOG2E * (a1[j] + ba1[j])), f1 = 1.f + fexp2(-LOG2E * (s1[j] + bs1[j]));
;                         a0[j] = f0 * frcp(e0); s0[j] = frcp(f0); a1[j] = f1 * frcp(e1); s1[j] = frcp(f1); }
;                     v4u w; w.x = pg8::cvt_pk_bf16(a0[0], a0[1]); w.y = pg8::cvt_pk_bf16(a0[2], a0[3]); w.z = pg8::cvt_pk_bf16(a1[0], a1[1]); w.w = pg8::cvt_pk_bf16(a1[2], a1[3]);
;                     __builtin_nontemporal_store(w, (v4u*)(GA + (size_t)row * 1024 + ch));
;                     w.x = pg8::cvt_pk_bf16(s0[0], s0[1]); w.y = pg8::cvt_pk_bf16(s0[2], s0[3]); w.z = pg8::cvt_pk_bf16(s1[0], s1[1]); w.w = pg8::cvt_pk_bf16(s1[2], s1[3]);
;                     __builtin_nontemporal_store(w, (v4u*)(GS + (size_t)row * 1024 + ch));
;                 }
	v_cvt_pk_bf16_f32 v63, v64, v65
	v_cvt_pk_bf16_f32 v64, v58, v59
	v_cvt_pk_bf16_f32 v65, v60, v61
	global_store_dwordx4 v[238:239], v[62:65], off nt
	v_lshl_add_u64 v[22:23], v[22:23], 0, s[0:1]
	v_lshl_add_u64 v[24:25], s[24:25], 0, v[22:23]
	v_lshl_add_u64 v[238:239], s[26:27], 0, v[22:23]
	v_pk_fma_f32 v[54:55], v[54:55], v[236:237], v[14:15] op_sel_hi:[1,0,1]
	v_pk_fma_f32 v[56:57], v[56:57], v[236:237], v[16:17] op_sel_hi:[1,0,1]
	v_pk_fma_f32 v[50:51], v[50:51], v[236:237], v[6:7] op_sel_hi:[1,0,1]
	v_pk_fma_f32 v[52:53], v[52:53], v[236:237], v[8:9] op_sel_hi:[1,0,1]
	v_pk_fma_f32 v[46:47], v[46:47], v[236:237], v[10:11] op_sel_hi:[1,0,1]
	v_pk_fma_f32 v[48:49], v[48:49], v[236:237], v[12:13] op_sel_hi:[1,0,1]
	v_pk_fma_f32 v[42:43], v[42:43], v[236:237], v[2:3] op_sel_hi:[1,0,1]
	v_pk_fma_f32 v[44:45], v[44:45], v[236:237], v[4:5] op_sel_hi:[1,0,1]
	v_exp_f32_e32 v54, v54
	v_exp_f32_e32 v55, v55
	v_exp_f32_e32 v56, v56
	v_exp_f32_e32 v57, v57
	v_exp_f32_e32 v50, v50
	v_exp_f32_e32 v51, v51
	v_exp_f32_e32 v52, v52
	v_exp_f32_e32 v53, v53
	v_exp_f32_e32 v46, v46
	v_exp_f32_e32 v47, v47
	v_exp_f32_e32 v48, v48
	v_exp_f32_e32 v49, v49
	v_exp_f32_e32 v42, v42
	v_exp_f32_e32 v43, v43
	v_exp_f32_e32 v44, v44
	v_exp_f32_e32 v45, v45
	v_pk_add_f32 v[54:55], v[54:55], 1.0 op_sel_hi:[1,0]
	v_pk_add_f32 v[56:57], v[56:57], 1.0 op_sel_hi:[1,0]
	v_pk_add_f32 v[50:51], v[50:51], 1.0 op_sel_hi:[1,0]
	v_pk_add_f32 v[52:53], v[52:53], 1.0 op_sel_hi:[1,0]
	v_pk_add_f32 v[46:47], v[46:47], 1.0 op_sel_hi:[1,0]
	v_pk_add_f32 v[48:49], v[48:49], 1.0 op_sel_hi:[1,0]
	v_pk_add_f32 v[42:43], v[42:43], 1.0 op_sel_hi:[1,0]
	v_pk_add_f32 v[44:45], v[44:45], 1.0 op_sel_hi:[1,0]
	v_rcp_f32_e32 v54, v54
	v_rcp_f32_e32 v55, v55
	v_rcp_f32_e32 v56, v56
	v_rcp_f32_e32 v57, v57
	v_rcp_f32_e32 v50, v50
	v_rcp_f32_e32 v51, v51
	v_rcp_f32_e32 v52, v52
	v_rcp_f32_e32 v53, v53
	v_pk_mul_f32 v[54:55], v[46:47], v[54:55]
	v_pk_mul_f32 v[56:57], v[48:49], v[56:57]
	v_pk_mul_f32 v[50:51], v[42:43], v[50:51]
	v_pk_mul_f32 v[52:53], v[44:45], v[52:53]
	v_rcp_f32_e32 v46, v46
	v_rcp_f32_e32 v47, v47
	v_rcp_f32_e32 v48, v48
	v_rcp_f32_e32 v49, v49
	v_rcp_f32_e32 v42, v42
	v_rcp_f32_e32 v43, v43
	v_rcp_f32_e32 v44, v44
	v_rcp_f32_e32 v45, v45
	v_cvt_pk_bf16_f32 v54, v54, v55
	v_cvt_pk_bf16_f32 v55, v56, v57
	v_cvt_pk_bf16_f32 v56, v50, v51
	v_cvt_pk_bf16_f32 v57, v52, v53
	global_store_dwordx4 v[24:25], v[54:57], off nt
	v_cvt_pk_bf16_f32 v46, v46, v47
	v_cvt_pk_bf16_f32 v47, v48, v49
	v_cvt_pk_bf16_f32 v48, v42, v43
	v_cvt_pk_bf16_f32 v49, v44, v45
	global_store_dwordx4 v[238:239], v[46:49], off nt
	v_lshl_add_u64 v[22:23], v[22:23], 0, s[0:1]
	v_lshl_add_u64 v[24:25], s[24:25], 0, v[22:23]
	v_lshl_add_u64 v[238:239], s[26:27], 0, v[22:23]
	v_pk_fma_f32 v[38:39], v[38:39], v[236:237], v[14:15] op_sel_hi:[1,0,1]
	v_pk_fma_f32 v[40:41], v[40:41], v[236:237], v[16:17] op_sel_hi:[1,0,1]
	v_pk_fma_f32 v[34:35], v[34:35], v[236:237], v[6:7] op_sel_hi:[1,0,1]
	v_pk_fma_f32 v[36:37], v[36:37], v[236:237], v[8:9] op_sel_hi:[1,0,1]
	v_pk_fma_f32 v[30:31], v[30:31], v[236:237], v[10:11] op_sel_hi:[1,0,1]
	v_pk_fma_f32 v[32:33], v[32:33], v[236:237], v[12:13] op_sel_hi:[1,0,1]
	v_pk_fma_f32 v[26:27], v[26:27], v[236:237], v[2:3] op_sel_hi:[1,0,1]
	v_pk_fma_f32 v[28:29], v[28:29], v[236:237], v[4:5] op_sel_hi:[1,0,1]
	v_exp_f32_e32 v38, v38
	v_exp_f32_e32 v39, v39
	v_exp_f32_e32 v40, v40
	v_exp_f32_e32 v41, v41
	v_exp_f32_e32 v34, v34
	v_exp_f32_e32 v35, v35
	v_exp_f32_e32 v36, v36
	v_exp_f32_e32 v37, v37
	v_exp_f32_e32 v30, v30
	v_exp_f32_e32 v31, v31
	v_exp_f32_e32 v32, v32
	v_exp_f32_e32 v33, v33
	v_exp_f32_e32 v26, v26
	v_exp_f32_e32 v27, v27
	v_exp_f32_e32 v28, v28
	v_exp_f32_e32 v29, v29
	v_pk_add_f32 v[38:39], v[38:39], 1.0 op_sel_hi:[1,0]
	v_pk_add_f32 v[40:41], v[40:41], 1.0 op_sel_hi:[1,0]
	v_pk_add_f32 v[34:35], v[34:35], 1.0 op_sel_hi:[1,0]
	v_pk_add_f32 v[36:37], v[36:37], 1.0 op_sel_hi:[1,0]
	v_pk_add_f32 v[30:31], v[30:31], 1.0 op_sel_hi:[1,0]
	v_pk_add_f32 v[32:33], v[32:33], 1.0 op_sel_hi:[1,0]
	v_pk_add_f32 v[26:27], v[26:27], 1.0 op_sel_hi:[1,0]
	v_pk_add_f32 v[28:29], v[28:29], 1.0 op_sel_hi:[1,0]
	v_rcp_f32_e32 v38, v38
	v_rcp_f32_e32 v39, v39
	v_rcp_f32_e32 v40, v40
	v_rcp_f32_e32 v41, v41
	v_rcp_f32_e32 v34, v34
	v_rcp_f32_e32 v35, v35
	v_rcp_f32_e32 v36, v36
	v_rcp_f32_e32 v37, v37
	v_pk_mul_f32 v[38:39], v[30:31], v[38:39]
	v_pk_mul_f32 v[40:41], v[32:33], v[40:41]
	v_pk_mul_f32 v[34:35], v[26:27], v[34:35]
	v_pk_mul_f32 v[36:37], v[28:29], v[36:37]
	v_rcp_f32_e32 v30, v30
	v_rcp_f32_e32 v31, v31
	v_rcp_f32_e32 v32, v32
	v_rcp_f32_e32 v33, v33
	v_rcp_f32_e32 v26, v26
	v_rcp_f32_e32 v27, v27
	v_rcp_f32_e32 v28, v28
	v_rcp_f32_e32 v29, v29
	v_cvt_pk_bf16_f32 v38, v38, v39
	v_cvt_pk_bf16_f32 v39, v40, v41
	v_cvt_pk_bf16_f32 v40, v34, v35
	v_cvt_pk_bf16_f32 v41, v36, v37
	global_store_dwordx4 v[24:25], v[38:41], off nt
	v_cvt_pk_bf16_f32 v30, v30, v31
	v_cvt_pk_bf16_f32 v31, v32, v33
	v_cvt_pk_bf16_f32 v32, v26, v27
	v_cvt_pk_bf16_f32 v33, v28, v29
	global_store_dwordx4 v[238:239], v[30:33], off nt
	s_andn2_b64 vcc, exec, s[52:53]
	s_mov_b64 s[0:1], -1
	s_cbranch_vccnz .LBB0_325
